# v59 + whole-kernel code placement shifted by 32 bytes (8 s_nop executed once at entry): hot GEMM/attention loops land on a better fetch phase
# speedup vs baseline: 1.0055x; 1.0055x over previous
_Z8mega_fwd4Args:
	s_nop 0
	s_nop 0
	s_nop 0
	s_nop 0
	s_nop 0
	s_nop 0
	s_nop 0
	s_nop 0
	s_mov_b64 s[70:71], s[0:1]
	s_load_dword s86, s[70:71], 0x128
	v_lshl_add_u32 v1, v0, 2, 0
	s_add_u32 s80, s70, 0x128
	v_add_u32_e32 v1, 0x20000, v1
	v_mov_b32_e32 v2, 0
	s_mov_b32 s82, s2
	v_readfirstlane_b32 s0, v0
	s_addc_u32 s81, s71, 0
	ds_write2st64_b32 v1, v2, v2 offset1:8
	ds_write2st64_b32 v1, v2, v2 offset0:16 offset1:24
	v_or_b32_e32 v1, 0x800, v0
	s_mov_b64 s[2:3], -1
	s_and_saveexec_b64 s[4:5], s[2:3]
	v_lshl_add_u32 v3, v1, 2, 0
	v_add_u32_e32 v3, 0x20000, v3
	ds_write_b32 v3, v2
	s_or_b64 exec, exec, s[4:5]
	s_and_saveexec_b64 s[4:5], s[2:3]
	s_add_i32 s1, 0, 0x20000
	v_lshl_add_u32 v1, v1, 2, s1
	v_mov_b32_e32 v2, 0
	ds_write_b32 v1, v2 offset:2048
	s_or_b64 exec, exec, s[4:5]
	s_load_dwordx2 s[72:73], s[70:71], 0xf8
	v_or_b32_e32 v1, 0xc00, v0
	v_cmp_gt_u32_e64 s[2:3], 7, 6
	v_cmp_gt_u32_e64 s[6:7], 7, 5
	s_and_saveexec_b64 s[4:5], s[6:7]
	v_lshl_add_u32 v2, v1, 2, 0
	v_add_u32_e32 v2, 0x20000, v2
	v_mov_b32_e32 v3, 0
	ds_write_b32 v2, v3
	s_or_b64 exec, exec, s[4:5]
	s_and_saveexec_b64 s[4:5], s[2:3]
	s_add_i32 s1, 0, 0x20000
	v_lshl_add_u32 v1, v1, 2, s1
	v_mov_b32_e32 v2, 0
	ds_write_b32 v1, v2 offset:2048
	s_or_b64 exec, exec, s[4:5]
	s_waitcnt lgkmcnt(0)
	s_barrier
	s_add_u32 s78, s72, 0x4000
	s_getreg_b32 s1, hwreg(HW_REG_XCC_ID, 0, 4)
	s_addc_u32 s79, s73, 0
	s_and_b32 s67, s1, 15
	v_cmp_eq_u32_e64 s[84:85], 0, v0
	s_and_saveexec_b64 s[2:3], s[84:85]
	s_cbranch_execz .LBB0_11
	s_mov_b64 s[4:5], exec
	v_mbcnt_lo_u32_b32 v1, s4, 0
	v_mbcnt_hi_u32_b32 v1, s5, v1
	v_cmp_eq_u32_e32 vcc, 0, v1
	s_and_b64 s[6:7], exec, vcc
	s_mov_b64 exec, s[6:7]
	s_cbranch_execz .LBB0_11
	s_lshl_b32 s1, s67, 8
	s_bcnt1_i32_b64 s4, s[4:5]
	v_mov_b32_e32 v1, s1
	v_mov_b32_e32 v2, s4
	global_atomic_add v1, v2, s[78:79] offset:1024
